# adds SWA bias-gather and PV LDS reads de-serialized (unconditional gathers w/ -inf sentinel, batched reads), retention: V reads hoisted in jt loop, cross-term reads double-buffered
# speedup vs baseline: 1.0041x; 1.0041x over previous
.LBB0_60:
	s_or_b64 exec, exec, s[34:35]
	v_readlane_b32 s24, v252, 29
	s_waitcnt vmcnt(1)
	ds_write_b128 v66, v[4:7]
	s_waitcnt vmcnt(0)
	ds_write_b16 v58, v0 offset:36864
	ds_write_b16_d16_hi v58, v0 offset:37392
	ds_write_b16 v58, v1 offset:37920
	ds_write_b16_d16_hi v58, v1 offset:38448
	ds_write_b16 v58, v2 offset:38976
	ds_write_b16_d16_hi v58, v2 offset:39504
	ds_write_b16 v58, v3 offset:40032
	ds_write_b16_d16_hi v58, v3 offset:40560
	v_mov_b32_e32 v0, s24
	v_mov_b32_e32 v90, 0x12430
	v_mov_b32_e32 v91, 0xff800000
	v_mov_b32_e32 v92, 0x12230
	ds_write_b32 v90, v91
	s_waitcnt lgkmcnt(0)
	s_barrier
	ds_read_b32 v67, v0
	v_lshl_or_b32 v0, s19, 7, v181
	v_or_b32_e32 v12, s28, v0
	s_lshl_b32 s24, s54, 9
	v_readlane_b32 s28, v254, 53
	s_add_i32 s24, s24, s28
	v_mov_b32_e32 v13, s29
	s_lshl_b64 s[28:29], s[24:25], 1
	v_lshl_add_u64 v[32:33], v[16:17], 0, s[28:29]
	v_lshl_add_u64 v[34:35], v[20:21], 0, s[28:29]
	s_branch .LBB0_62
.LBB0_61:
	s_or_b64 exec, exec, s[28:29]
	v_max3_f32 v0, v67, v40, v38
	v_max3_f32 v0, v0, v43, v42
	v_max3_f32 v0, v0, v45, v44
	v_max3_f32 v0, v0, v47, v46
	v_max3_f32 v0, v0, v49, v48
	v_max3_f32 v0, v0, v51, v50
	v_max3_f32 v0, v0, v53, v52
	v_max3_f32 v0, v0, v69, v68
	v_max3_f32 v0, v0, v71, v70
	v_max3_f32 v0, v0, v73, v72
	v_max3_f32 v0, v0, v75, v74
	v_max3_f32 v0, v0, v77, v76
	v_max3_f32 v0, v0, v79, v78
	v_max3_f32 v0, v0, v81, v80
	v_max3_f32 v0, v0, v83, v82
	v_max3_f32 v0, v0, v85, v84
	v_max3_f32 v0, v0, v87, v86
	v_max3_f32 v0, v0, v89, v88
	v_mov_b32_e32 v1, v0
	s_nop 1
	v_permlane16_swap_b32_e32 v0, v1
	v_max_f32_e32 v1, v1, v1
	v_max_f32_e32 v0, v0, v0
	v_max_f32_e32 v0, v0, v1
	v_mov_b32_e32 v1, v0
	s_nop 1
	v_permlane32_swap_b32_e32 v0, v1
	v_max_f32_e32 v1, v1, v1
	v_max_f32_e32 v0, v0, v0
	v_max_f32_e32 v41, v0, v1
	v_sub_f32_e32 v0, v40, v41
	v_mul_f32_e32 v0, 0x3fb8aa3b, v0
	v_sub_f32_e32 v1, v38, v41
	v_exp_f32_e32 v0, v0
	v_mul_f32_e32 v1, 0x3fb8aa3b, v1
	v_exp_f32_e32 v1, v1
	s_cmp_eq_u32 s24, 8
	v_add_f32_e32 v2, 0, v0
	v_add_f32_e32 v3, v2, v1
	v_sub_f32_e32 v2, v43, v41
	v_mul_f32_e32 v2, 0x3fb8aa3b, v2
	v_exp_f32_e32 v2, v2
	s_nop 0
	v_add_f32_e32 v4, v3, v2
	v_sub_f32_e32 v3, v42, v41
	v_mul_f32_e32 v3, 0x3fb8aa3b, v3
	v_exp_f32_e32 v3, v3
	v_sub_f32_e32 v42, v69, v41
	v_mul_f32_e32 v42, 0x3fb8aa3b, v42
	v_add_f32_e32 v5, v4, v3
	v_sub_f32_e32 v4, v45, v41
	v_mul_f32_e32 v4, 0x3fb8aa3b, v4
	v_exp_f32_e32 v4, v4
	s_nop 0
	v_add_f32_e32 v6, v5, v4
	v_sub_f32_e32 v5, v44, v41
	v_mul_f32_e32 v5, 0x3fb8aa3b, v5
	v_exp_f32_e32 v5, v5
	s_nop 0
	v_add_f32_e32 v7, v6, v5
	v_sub_f32_e32 v6, v47, v41
	v_mul_f32_e32 v6, 0x3fb8aa3b, v6
	v_exp_f32_e32 v6, v6
	s_nop 0
	v_add_f32_e32 v8, v7, v6
	v_sub_f32_e32 v7, v46, v41
	v_mul_f32_e32 v7, 0x3fb8aa3b, v7
	v_exp_f32_e32 v7, v7
	v_exp_f32_e32 v46, v42
	v_sub_f32_e32 v42, v68, v41
	v_mul_f32_e32 v42, 0x3fb8aa3b, v42
	v_add_f32_e32 v9, v8, v7
	v_sub_f32_e32 v8, v49, v41
	v_mul_f32_e32 v8, 0x3fb8aa3b, v8
	v_exp_f32_e32 v8, v8
	v_exp_f32_e32 v47, v42
	v_sub_f32_e32 v42, v71, v41
	v_mul_f32_e32 v42, 0x3fb8aa3b, v42
	v_add_f32_e32 v10, v9, v8
	v_sub_f32_e32 v9, v48, v41
	v_mul_f32_e32 v9, 0x3fb8aa3b, v9
	v_exp_f32_e32 v9, v9
	v_exp_f32_e32 v48, v42
	v_sub_f32_e32 v42, v70, v41
	v_mul_f32_e32 v42, 0x3fb8aa3b, v42
	v_add_f32_e32 v11, v10, v9
	v_sub_f32_e32 v10, v51, v41
	v_mul_f32_e32 v10, 0x3fb8aa3b, v10
	v_exp_f32_e32 v10, v10
	v_exp_f32_e32 v49, v42
	v_sub_f32_e32 v42, v73, v41
	v_mul_f32_e32 v42, 0x3fb8aa3b, v42
	v_add_f32_e32 v38, v11, v10
	v_sub_f32_e32 v11, v50, v41
	v_mul_f32_e32 v11, 0x3fb8aa3b, v11
	v_exp_f32_e32 v11, v11
	v_exp_f32_e32 v50, v42
	v_sub_f32_e32 v42, v72, v41
	v_mul_f32_e32 v42, 0x3fb8aa3b, v42
	v_add_f32_e32 v39, v38, v11
	v_sub_f32_e32 v38, v53, v41
	v_mul_f32_e32 v38, 0x3fb8aa3b, v38
	v_exp_f32_e32 v38, v38
	v_exp_f32_e32 v51, v42
	v_sub_f32_e32 v42, v75, v41
	v_mul_f32_e32 v42, 0x3fb8aa3b, v42
	v_add_f32_e32 v40, v39, v38
	v_sub_f32_e32 v39, v52, v41
	v_exp_f32_e32 v52, v42
	v_sub_f32_e32 v42, v74, v41
	v_mul_f32_e32 v42, 0x3fb8aa3b, v42
	v_exp_f32_e32 v53, v42
	v_sub_f32_e32 v42, v77, v41
	v_mul_f32_e32 v42, 0x3fb8aa3b, v42
	v_exp_f32_e32 v68, v42
	v_sub_f32_e32 v42, v76, v41
	v_mul_f32_e32 v42, 0x3fb8aa3b, v42
	v_exp_f32_e32 v69, v42
	v_sub_f32_e32 v42, v79, v41
	v_mul_f32_e32 v39, 0x3fb8aa3b, v39
	v_mul_f32_e32 v42, 0x3fb8aa3b, v42
	v_exp_f32_e32 v39, v39
	v_exp_f32_e32 v70, v42
	v_sub_f32_e32 v42, v78, v41
	v_mul_f32_e32 v42, 0x3fb8aa3b, v42
	v_exp_f32_e32 v71, v42
	v_sub_f32_e32 v42, v81, v41
	v_mul_f32_e32 v42, 0x3fb8aa3b, v42
	v_add_f32_e32 v40, v40, v39
	v_exp_f32_e32 v72, v42
	v_sub_f32_e32 v42, v80, v41
	v_add_f32_e32 v40, v40, v46
	v_mul_f32_e32 v42, 0x3fb8aa3b, v42
	v_add_f32_e32 v40, v40, v47
	v_exp_f32_e32 v73, v42
	v_sub_f32_e32 v42, v83, v41
	v_add_f32_e32 v40, v40, v48
	v_mul_f32_e32 v42, 0x3fb8aa3b, v42
	v_add_f32_e32 v40, v40, v49
	v_exp_f32_e32 v74, v42
	v_sub_f32_e32 v42, v82, v41
	v_add_f32_e32 v40, v40, v50
	v_mul_f32_e32 v42, 0x3fb8aa3b, v42
	v_add_f32_e32 v40, v40, v51
	v_exp_f32_e32 v75, v42
	v_sub_f32_e32 v42, v85, v41
	v_add_f32_e32 v40, v40, v52
	v_mul_f32_e32 v42, 0x3fb8aa3b, v42
	v_add_f32_e32 v40, v40, v53
	v_exp_f32_e32 v76, v42
	v_sub_f32_e32 v42, v84, v41
	v_add_f32_e32 v40, v40, v68
	v_mul_f32_e32 v42, 0x3fb8aa3b, v42
	v_add_f32_e32 v40, v40, v69
	v_exp_f32_e32 v77, v42
	v_sub_f32_e32 v42, v87, v41
	v_add_f32_e32 v40, v40, v70
	v_mul_f32_e32 v42, 0x3fb8aa3b, v42
	v_add_f32_e32 v40, v40, v71
	v_exp_f32_e32 v78, v42
	v_sub_f32_e32 v42, v86, v41
	v_add_f32_e32 v40, v40, v72
	v_mul_f32_e32 v42, 0x3fb8aa3b, v42
	v_add_f32_e32 v40, v40, v73
	v_exp_f32_e32 v79, v42
	v_sub_f32_e32 v42, v89, v41
	v_add_f32_e32 v40, v40, v74
	v_mul_f32_e32 v42, 0x3fb8aa3b, v42
	v_add_f32_e32 v40, v40, v75
	v_exp_f32_e32 v80, v42
	v_sub_f32_e32 v42, v88, v41
	v_add_f32_e32 v40, v40, v76
	v_mul_f32_e32 v42, 0x3fb8aa3b, v42
	v_add_f32_e32 v40, v40, v77
	v_exp_f32_e32 v81, v42
	v_add_f32_e32 v40, v40, v78
	v_add_f32_e32 v40, v40, v79
	v_add_f32_e32 v40, v40, v80
	v_add_f32_e32 v40, v40, v81
	v_mov_b32_e32 v42, v40
	v_sub_f32_e32 v41, v67, v41
	s_nop 0
	v_permlane16_swap_b32_e32 v40, v42
	v_mul_f32_e32 v41, 0x3fb8aa3b, v41
	v_add_f32_e32 v40, v40, v42
	v_exp_f32_e32 v41, v41
	v_mov_b32_e32 v42, v40
	s_nop 1
	v_permlane32_swap_b32_e32 v40, v42
	v_add_f32_e32 v40, v40, v42
	v_add_f32_e32 v40, v41, v40
	v_div_scale_f32 v41, s[28:29], v40, v40, 1.0
	v_rcp_f32_e32 v42, v41
	s_nop 0
	v_fma_f32 v43, -v41, v42, 1.0
	v_fmac_f32_e32 v42, v43, v42
	v_div_scale_f32 v43, vcc, 1.0, v40, 1.0
	v_mul_f32_e32 v44, v43, v42
	v_fma_f32 v45, -v41, v44, v43
	v_fmac_f32_e32 v44, v45, v42
	v_fma_f32 v41, -v41, v44, v43
	v_div_fmas_f32 v41, v41, v42, v44
	v_div_fixup_f32 v82, v41, v40, 1.0
	v_pk_mul_f32 v[0:1], v[82:83], v[0:1] op_sel_hi:[0,1]
	v_cvt_pk_bf16_f32 v44, v0, v1
	v_pk_mul_f32 v[0:1], v[82:83], v[2:3] op_sel_hi:[0,1]
	v_cvt_pk_bf16_f32 v45, v0, v1
	v_pk_mul_f32 v[0:1], v[82:83], v[4:5] op_sel_hi:[0,1]
	v_cvt_pk_bf16_f32 v42, v0, v1
	v_pk_mul_f32 v[0:1], v[82:83], v[6:7] op_sel_hi:[0,1]
	v_cvt_pk_bf16_f32 v43, v0, v1
	v_pk_mul_f32 v[0:1], v[82:83], v[8:9] op_sel_hi:[0,1]
	v_cvt_pk_bf16_f32 v40, v0, v1
	v_pk_mul_f32 v[0:1], v[82:83], v[10:11] op_sel_hi:[0,1]
	v_cvt_pk_bf16_f32 v41, v0, v1
	v_pk_mul_f32 v[0:1], v[82:83], v[38:39] op_sel_hi:[0,1]
	v_cvt_pk_bf16_f32 v38, v0, v1
	v_pk_mul_f32 v[0:1], v[82:83], v[46:47] op_sel_hi:[0,1]
	v_cvt_pk_bf16_f32 v39, v0, v1
	v_pk_mul_f32 v[0:1], v[82:83], v[48:49] op_sel_hi:[0,1]
	v_cvt_pk_bf16_f32 v10, v0, v1
	v_pk_mul_f32 v[0:1], v[82:83], v[50:51] op_sel_hi:[0,1]
	v_cvt_pk_bf16_f32 v11, v0, v1
	v_pk_mul_f32 v[0:1], v[82:83], v[52:53] op_sel_hi:[0,1]
	v_cvt_pk_bf16_f32 v8, v0, v1
	v_pk_mul_f32 v[0:1], v[82:83], v[68:69] op_sel_hi:[0,1]
	v_cvt_pk_bf16_f32 v9, v0, v1
	v_pk_mul_f32 v[0:1], v[82:83], v[70:71] op_sel_hi:[0,1]
	v_cvt_pk_bf16_f32 v6, v0, v1
	v_pk_mul_f32 v[0:1], v[82:83], v[72:73] op_sel_hi:[0,1]
	v_cvt_pk_bf16_f32 v7, v0, v1
	v_pk_mul_f32 v[0:1], v[82:83], v[74:75] op_sel_hi:[0,1]
	v_cvt_pk_bf16_f32 v4, v0, v1
	v_pk_mul_f32 v[0:1], v[82:83], v[76:77] op_sel_hi:[0,1]
	v_cvt_pk_bf16_f32 v5, v0, v1
	v_pk_mul_f32 v[0:1], v[82:83], v[78:79] op_sel_hi:[0,1]
	v_cvt_pk_bf16_f32 v2, v0, v1
	v_pk_mul_f32 v[0:1], v[82:83], v[80:81] op_sel_hi:[0,1]
	v_lshl_add_u32 v50, s36, 5, v59
	v_cvt_pk_bf16_f32 v3, v0, v1
	v_lshlrev_b64 v[0:1], 11, v[36:37]
	v_lshl_add_u32 v51, s24, 5, v59
	v_lshl_add_u32 v52, s37, 5, v59
	v_lshl_add_u32 v53, s54, 5, v59
	v_lshl_add_u32 v68, s55, 5, v59
	v_lshl_add_u32 v69, s57, 5, v59
	v_lshl_add_u32 v70, s58, 5, v59
	v_lshl_add_u32 v71, s59, 5, v59
	v_lshl_add_u32 v72, s34, 5, v59
	ds_read_b64 v[96:97], v50 offset:36864
	ds_read_b64 v[98:99], v51 offset:36864
	ds_read_b64 v[100:101], v52 offset:36864
	ds_read_b64 v[102:103], v53 offset:36864
	ds_read_b64 v[104:105], v68 offset:36864
	ds_read_b64 v[106:107], v69 offset:36864
	ds_read_b64 v[108:109], v70 offset:36864
	ds_read_b64 v[110:111], v71 offset:36864
	ds_read_b64 v[112:113], v72 offset:36864
	s_waitcnt lgkmcnt(0)
	ds_read_b64 v[114:115], v50 offset:45312
	ds_read_b64 v[116:117], v51 offset:45312
	ds_read_b64 v[118:119], v52 offset:45312
	ds_read_b64 v[120:121], v53 offset:45312
	ds_read_b64 v[122:123], v68 offset:45312
	ds_read_b64 v[126:127], v69 offset:45312
	ds_read_b64 v[128:129], v70 offset:45312
	ds_read_b64 v[130:131], v71 offset:45312
	ds_read_b64 v[132:133], v72 offset:45312
	v_lshl_add_u32 v51, s24, 5, v59
	v_mfma_f32_16x16x16_bf16 v[46:49], v[96:97], v[44:45], 0
	v_lshl_add_u32 v52, s37, 5, v59
	v_lshl_add_u32 v53, s54, 5, v59
	v_mfma_f32_16x16x16_bf16 v[46:49], v[98:99], v[42:43], v[46:49]
	v_lshl_add_u32 v68, s55, 5, v59
	v_lshl_add_u32 v69, s57, 5, v59
	v_mfma_f32_16x16x16_bf16 v[46:49], v[100:101], v[40:41], v[46:49]
	v_lshl_add_u32 v70, s58, 5, v59
	v_lshl_add_u32 v71, s59, 5, v59
	v_mfma_f32_16x16x16_bf16 v[46:49], v[102:103], v[38:39], v[46:49]
	v_lshl_add_u32 v72, s34, 5, v59
	v_lshl_add_u64 v[0:1], v[34:35], 0, v[0:1]
	v_mfma_f32_16x16x16_bf16 v[46:49], v[104:105], v[10:11], v[46:49]
	s_mov_b32 s36, s24
	v_mfma_f32_16x16x16_bf16 v[46:49], v[106:107], v[8:9], v[46:49]
	v_mfma_f32_16x16x16_bf16 v[46:49], v[108:109], v[6:7], v[46:49]
	v_mfma_f32_16x16x16_bf16 v[46:49], v[110:111], v[4:5], v[46:49]
	v_mfma_f32_16x16x16_bf16 v[46:49], v[112:113], v[2:3], v[46:49]
	s_nop 7
	v_cvt_pk_bf16_f32 v36, v46, v47
	v_cvt_pk_bf16_f32 v37, v48, v49
	global_store_dwordx2 v[0:1], v[36:37], off
	s_waitcnt lgkmcnt(0)
	ds_read_b64 v[96:97], v50 offset:53760
	ds_read_b64 v[98:99], v51 offset:53760
	ds_read_b64 v[100:101], v52 offset:53760
	ds_read_b64 v[102:103], v53 offset:53760
	ds_read_b64 v[104:105], v68 offset:53760
	ds_read_b64 v[106:107], v69 offset:53760
	ds_read_b64 v[108:109], v70 offset:53760
	ds_read_b64 v[110:111], v71 offset:53760
	ds_read_b64 v[112:113], v72 offset:53760
	v_mfma_f32_16x16x16_bf16 v[46:49], v[114:115], v[44:45], 0
	v_mfma_f32_16x16x16_bf16 v[46:49], v[116:117], v[42:43], v[46:49]
	v_mfma_f32_16x16x16_bf16 v[46:49], v[118:119], v[40:41], v[46:49]
	v_mfma_f32_16x16x16_bf16 v[46:49], v[120:121], v[38:39], v[46:49]
	v_mfma_f32_16x16x16_bf16 v[46:49], v[122:123], v[10:11], v[46:49]
	v_mfma_f32_16x16x16_bf16 v[46:49], v[126:127], v[8:9], v[46:49]
	v_mfma_f32_16x16x16_bf16 v[46:49], v[128:129], v[6:7], v[46:49]
	v_mfma_f32_16x16x16_bf16 v[46:49], v[130:131], v[4:5], v[46:49]
	v_mfma_f32_16x16x16_bf16 v[46:49], v[132:133], v[2:3], v[46:49]
	s_nop 7
	v_cvt_pk_bf16_f32 v36, v46, v47
	v_cvt_pk_bf16_f32 v37, v48, v49
	global_store_dwordx2 v[0:1], v[36:37], off offset:32
	s_waitcnt lgkmcnt(0)
	ds_read_b64 v[114:115], v50 offset:62208
	ds_read_b64 v[116:117], v51 offset:62208
	ds_read_b64 v[118:119], v52 offset:62208
	ds_read_b64 v[120:121], v53 offset:62208
	ds_read_b64 v[122:123], v68 offset:62208
	ds_read_b64 v[126:127], v69 offset:62208
	ds_read_b64 v[128:129], v70 offset:62208
	ds_read_b64 v[130:131], v71 offset:62208
	ds_read_b64 v[132:133], v72 offset:62208
	v_mfma_f32_16x16x16_bf16 v[46:49], v[96:97], v[44:45], 0
	v_mfma_f32_16x16x16_bf16 v[46:49], v[98:99], v[42:43], v[46:49]
	v_mfma_f32_16x16x16_bf16 v[46:49], v[100:101], v[40:41], v[46:49]
	v_mfma_f32_16x16x16_bf16 v[46:49], v[102:103], v[38:39], v[46:49]
	v_mfma_f32_16x16x16_bf16 v[46:49], v[104:105], v[10:11], v[46:49]
	v_mfma_f32_16x16x16_bf16 v[46:49], v[106:107], v[8:9], v[46:49]
	v_mfma_f32_16x16x16_bf16 v[46:49], v[108:109], v[6:7], v[46:49]
	v_mfma_f32_16x16x16_bf16 v[46:49], v[110:111], v[4:5], v[46:49]
	v_mfma_f32_16x16x16_bf16 v[46:49], v[112:113], v[2:3], v[46:49]
	s_nop 7
	v_cvt_pk_bf16_f32 v36, v46, v47
	v_cvt_pk_bf16_f32 v37, v48, v49
	global_store_dwordx2 v[0:1], v[36:37], off offset:64
	s_waitcnt lgkmcnt(0)
	v_mfma_f32_16x16x16_bf16 v[44:47], v[114:115], v[44:45], 0
	v_mfma_f32_16x16x16_bf16 v[42:45], v[116:117], v[42:43], v[44:47]
	v_mfma_f32_16x16x16_bf16 v[40:43], v[118:119], v[40:41], v[42:45]
	v_mfma_f32_16x16x16_bf16 v[36:39], v[120:121], v[38:39], v[40:43]
	s_nop 4
	v_mfma_f32_16x16x16_bf16 v[36:39], v[122:123], v[10:11], v[36:39]
	v_mfma_f32_16x16x16_bf16 v[8:11], v[126:127], v[8:9], v[36:39]
	s_nop 4
	v_mfma_f32_16x16x16_bf16 v[6:9], v[128:129], v[6:7], v[8:11]
	s_nop 2
	v_mfma_f32_16x16x16_bf16 v[4:7], v[130:131], v[4:5], v[6:9]
	s_nop 2
	v_mfma_f32_16x16x16_bf16 v[2:5], v[132:133], v[2:3], v[4:7]
	s_nop 7
	v_cvt_pk_bf16_f32 v2, v2, v3
	v_cvt_pk_bf16_f32 v3, v4, v5
	global_store_dwordx2 v[0:1], v[2:3], off offset:96
	s_cbranch_scc1 .LBB0_39
.LBB0_62:
	s_lshl_b32 s24, s36, 4
	v_lshl_add_u64 v[36:37], v[12:13], 0, s[24:25]
	v_mad_u64_u32 v[0:1], s[28:29], v36, s84, v[32:33]
	v_mov_b32_e32 v2, v1
	v_mad_u64_u32 v[2:3], s[28:29], v37, s84, v[2:3]
	v_mov_b32_e32 v1, v2
	global_load_dwordx4 v[4:7], v[0:1], off
	s_nop 0
	global_load_dwordx4 v[0:3], v[0:1], off offset:64
	v_or_b32_e32 v39, s24, v181
	v_mad_u64_u32 v[42:43], s[28:29], v39, s99, v[18:19]
	ds_read_b128 v[8:11], v42
	ds_read_b128 v[42:45], v42 offset:64
	v_or_b32_e32 v41, 0x80, v39
	v_mov_b32_e32 v40, 0xff800000
	s_waitcnt vmcnt(1) lgkmcnt(1)
	v_mfma_f32_16x16x32_bf16 v[8:11], v[8:11], v[4:7], 0
	s_waitcnt vmcnt(0) lgkmcnt(0)
	v_mfma_f32_16x16x32_bf16 v[8:11], v[42:45], v[0:3], v[8:11]
	s_nop 7
	v_mov_b32_e32 v147, v8
	v_mov_b32_e32 v148, v9
	v_mov_b32_e32 v149, v10
	v_mov_b32_e32 v150, v11
	v_or_b32_e32 v44, s24, v54
	v_sub_u32_e32 v38, v41, v44
	v_cmp_gt_u32_e32 vcc, s76, v38
	s_and_b64 s[34:35], vcc, s[0:1]
	v_mov_b32_e32 v38, 0xff800000
	v_sub_u32_e32 v40, v39, v44
	v_lshl_add_u32 v40, v40, 2, s33
	v_cndmask_b32_e64 v40, v92, v40, s[34:35]
	ds_read_b32 v96, v40 offset:512
	v_not_b32_e32 v8, v44
	v_add_u32_e32 v42, v41, v8
	v_cmp_gt_u32_e32 vcc, s76, v42
	s_and_b64 s[34:35], vcc, s[0:1]
	v_add_u32_e32 v8, v39, v8
	v_lshl_add_u32 v8, v8, 2, s33
	v_cndmask_b32_e64 v8, v92, v8, s[34:35]
	ds_read_b32 v97, v8 offset:512
	v_or_b32_e32 v8, 2, v44
	v_sub_u32_e32 v9, v41, v8
	v_cmp_gt_u32_e32 vcc, s76, v9
	s_and_b64 s[34:35], vcc, s[0:1]
	v_mov_b32_e32 v42, 0xff800000
	v_mov_b32_e32 v43, 0xff800000
	v_sub_u32_e32 v8, v39, v8
	v_lshl_add_u32 v8, v8, 2, s33
	v_cndmask_b32_e64 v8, v92, v8, s[34:35]
	ds_read_b32 v98, v8 offset:512
	v_or_b32_e32 v8, 3, v44
	v_sub_u32_e32 v9, v41, v8
	v_cmp_gt_u32_e32 vcc, s76, v9
	s_and_b64 s[34:35], vcc, s[0:1]
	v_sub_u32_e32 v8, v39, v8
	v_lshl_add_u32 v8, v8, 2, s33
	v_cndmask_b32_e64 v8, v92, v8, s[34:35]
	ds_read_b32 v99, v8 offset:512
	s_add_i32 s24, s36, 1
	s_lshl_b32 s34, s24, 4
	v_or_b32_e32 v8, s34, v181
	v_mad_u64_u32 v[44:45], s[28:29], v8, s99, v[18:19]
	ds_read_b128 v[8:11], v44
	ds_read_b128 v[44:47], v44 offset:64
	v_or_b32_e32 v48, s34, v54
	s_cmp_gt_u32 s36, 6
	s_cselect_b64 s[28:29], -1, 0
	s_or_b64 s[28:29], s[0:1], s[28:29]
	s_waitcnt lgkmcnt(1)
	v_mfma_f32_16x16x32_bf16 v[8:11], v[8:11], v[4:7], 0
	s_waitcnt lgkmcnt(0)
	v_mfma_f32_16x16x32_bf16 v[8:11], v[44:47], v[0:3], v[8:11]
	s_nop 7
	v_mov_b32_e32 v151, v8
	v_mov_b32_e32 v152, v9
	v_mov_b32_e32 v153, v10
	v_mov_b32_e32 v154, v11
	v_sub_u32_e32 v44, v41, v48
	v_cmp_gt_u32_e32 vcc, s76, v44
	s_and_b64 s[54:55], vcc, s[28:29]
	v_mov_b32_e32 v44, 0xff800000
	v_mov_b32_e32 v45, 0xff800000
	v_sub_u32_e32 v45, v39, v48
	v_lshl_add_u32 v45, v45, 2, s33
	v_cndmask_b32_e64 v45, v92, v45, s[54:55]
	ds_read_b32 v100, v45 offset:512
	v_not_b32_e32 v8, v48
	v_add_u32_e32 v46, v41, v8
	v_cmp_gt_u32_e32 vcc, s76, v46
	s_and_b64 s[54:55], vcc, s[28:29]
	v_add_u32_e32 v8, v39, v8
	v_lshl_add_u32 v8, v8, 2, s33
	v_cndmask_b32_e64 v8, v92, v8, s[54:55]
	ds_read_b32 v101, v8 offset:512
	v_or_b32_e32 v8, 2, v48
	v_sub_u32_e32 v9, v41, v8
	v_cmp_gt_u32_e32 vcc, s76, v9
	s_and_b64 s[54:55], vcc, s[28:29]
	v_mov_b32_e32 v46, 0xff800000
	v_mov_b32_e32 v47, 0xff800000
	v_sub_u32_e32 v8, v39, v8
	v_lshl_add_u32 v8, v8, 2, s33
	v_cndmask_b32_e64 v8, v92, v8, s[54:55]
	ds_read_b32 v102, v8 offset:512
	v_or_b32_e32 v8, 3, v48
	v_sub_u32_e32 v9, v41, v8
	v_cmp_gt_u32_e32 vcc, s76, v9
	s_and_b64 s[34:35], vcc, s[28:29]
	v_sub_u32_e32 v8, v39, v8
	v_lshl_add_u32 v8, v8, 2, s33
	v_cndmask_b32_e64 v8, v92, v8, s[34:35]
	ds_read_b32 v103, v8 offset:512
	s_add_i32 s37, s36, 2
	s_lshl_b32 s34, s37, 4
	v_or_b32_e32 v8, s34, v181
	v_mad_u64_u32 v[48:49], s[28:29], v8, s99, v[18:19]
	ds_read_b128 v[8:11], v48
	ds_read_b128 v[48:51], v48 offset:64
	v_or_b32_e32 v52, s34, v54
	s_cmp_gt_u32 s36, 5
	s_cselect_b64 s[28:29], -1, 0
	s_or_b64 s[28:29], s[0:1], s[28:29]
	s_waitcnt lgkmcnt(1)
	v_mfma_f32_16x16x32_bf16 v[8:11], v[8:11], v[4:7], 0
	s_waitcnt lgkmcnt(0)
	v_mfma_f32_16x16x32_bf16 v[8:11], v[48:51], v[0:3], v[8:11]
	s_nop 7
	v_mov_b32_e32 v155, v8
	v_mov_b32_e32 v156, v9
	v_mov_b32_e32 v157, v10
	v_mov_b32_e32 v158, v11
	v_sub_u32_e32 v48, v41, v52
	v_cmp_gt_u32_e32 vcc, s76, v48
	s_and_b64 s[54:55], vcc, s[28:29]
	v_mov_b32_e32 v48, 0xff800000
	v_mov_b32_e32 v49, 0xff800000
	v_sub_u32_e32 v49, v39, v52
	v_lshl_add_u32 v49, v49, 2, s33
	v_cndmask_b32_e64 v49, v92, v49, s[54:55]
	ds_read_b32 v104, v49 offset:512
	v_not_b32_e32 v8, v52
	v_add_u32_e32 v50, v41, v8
	v_cmp_gt_u32_e32 vcc, s76, v50
	s_and_b64 s[54:55], vcc, s[28:29]
	v_add_u32_e32 v8, v39, v8
	v_lshl_add_u32 v8, v8, 2, s33
	v_cndmask_b32_e64 v8, v92, v8, s[54:55]
	ds_read_b32 v105, v8 offset:512
	v_or_b32_e32 v8, 2, v52
	v_sub_u32_e32 v9, v41, v8
	v_cmp_gt_u32_e32 vcc, s76, v9
	s_and_b64 s[54:55], vcc, s[28:29]
	v_mov_b32_e32 v50, 0xff800000
	v_mov_b32_e32 v51, 0xff800000
	v_sub_u32_e32 v8, v39, v8
	v_lshl_add_u32 v8, v8, 2, s33
	v_cndmask_b32_e64 v8, v92, v8, s[54:55]
	ds_read_b32 v106, v8 offset:512
	v_or_b32_e32 v8, 3, v52
	v_sub_u32_e32 v9, v41, v8
	v_cmp_gt_u32_e32 vcc, s76, v9
	s_and_b64 s[34:35], vcc, s[28:29]
	v_sub_u32_e32 v8, v39, v8
	v_lshl_add_u32 v8, v8, 2, s33
	v_cndmask_b32_e64 v8, v92, v8, s[34:35]
	ds_read_b32 v107, v8 offset:512
	s_add_i32 s54, s36, 3
	s_lshl_b32 s34, s54, 4
	v_or_b32_e32 v8, s34, v181
	v_mad_u64_u32 v[52:53], s[28:29], v8, s99, v[18:19]
	ds_read_b128 v[8:11], v52
	ds_read_b128 v[68:71], v52 offset:64
	s_cmp_gt_u32 s36, 4
	s_cselect_b64 s[28:29], -1, 0
	s_or_b64 s[28:29], s[0:1], s[28:29]
	v_mov_b32_e32 v53, 0xff800000
	s_waitcnt lgkmcnt(1)
	v_mfma_f32_16x16x32_bf16 v[8:11], v[8:11], v[4:7], 0
	s_waitcnt lgkmcnt(0)
	v_mfma_f32_16x16x32_bf16 v[8:11], v[68:71], v[0:3], v[8:11]
	s_nop 7
	v_mov_b32_e32 v159, v8
	v_mov_b32_e32 v160, v9
	v_mov_b32_e32 v161, v10
	v_mov_b32_e32 v162, v11
	v_or_b32_e32 v70, s34, v54
	v_sub_u32_e32 v52, v41, v70
	v_cmp_gt_u32_e32 vcc, s76, v52
	s_and_b64 s[58:59], vcc, s[28:29]
	v_mov_b32_e32 v52, 0xff800000
	v_sub_u32_e32 v53, v39, v70
	v_lshl_add_u32 v53, v53, 2, s33
	v_cndmask_b32_e64 v53, v92, v53, s[58:59]
	ds_read_b32 v108, v53 offset:512
	v_not_b32_e32 v8, v70
	v_add_u32_e32 v68, v41, v8
	v_cmp_gt_u32_e32 vcc, s76, v68
	s_and_b64 s[58:59], vcc, s[28:29]
	v_add_u32_e32 v8, v39, v8
	v_lshl_add_u32 v8, v8, 2, s33
	v_cndmask_b32_e64 v8, v92, v8, s[58:59]
	ds_read_b32 v109, v8 offset:512
	v_or_b32_e32 v8, 2, v70
	v_sub_u32_e32 v9, v41, v8
	v_cmp_gt_u32_e32 vcc, s76, v9
	s_and_b64 s[58:59], vcc, s[28:29]
	v_mov_b32_e32 v68, 0xff800000
	v_mov_b32_e32 v69, 0xff800000
	v_sub_u32_e32 v8, v39, v8
	v_lshl_add_u32 v8, v8, 2, s33
	v_cndmask_b32_e64 v8, v92, v8, s[58:59]
	ds_read_b32 v110, v8 offset:512
	v_or_b32_e32 v8, 3, v70
	v_sub_u32_e32 v9, v41, v8
	v_cmp_gt_u32_e32 vcc, s76, v9
	s_and_b64 s[34:35], vcc, s[28:29]
	v_sub_u32_e32 v8, v39, v8
	v_lshl_add_u32 v8, v8, 2, s33
	v_cndmask_b32_e64 v8, v92, v8, s[34:35]
	ds_read_b32 v111, v8 offset:512
	s_add_i32 s55, s36, 4
	s_lshl_b32 s34, s55, 4
	v_or_b32_e32 v8, s34, v181
	v_mad_u64_u32 v[70:71], s[28:29], v8, s99, v[18:19]
	ds_read_b128 v[8:11], v70
	ds_read_b128 v[70:73], v70 offset:64
	v_or_b32_e32 v74, s34, v54
	s_cmp_gt_u32 s36, 3
	s_cselect_b64 s[28:29], -1, 0
	s_or_b64 s[28:29], s[0:1], s[28:29]
	s_waitcnt lgkmcnt(1)
	v_mfma_f32_16x16x32_bf16 v[8:11], v[8:11], v[4:7], 0
	s_waitcnt lgkmcnt(0)
	v_mfma_f32_16x16x32_bf16 v[8:11], v[70:73], v[0:3], v[8:11]
	s_nop 7
	v_mov_b32_e32 v163, v8
	v_mov_b32_e32 v164, v9
	v_mov_b32_e32 v165, v10
	v_mov_b32_e32 v166, v11
	v_sub_u32_e32 v70, v41, v74
	v_cmp_gt_u32_e32 vcc, s76, v70
	s_and_b64 s[58:59], vcc, s[28:29]
	v_mov_b32_e32 v70, 0xff800000
	v_mov_b32_e32 v71, 0xff800000
	v_sub_u32_e32 v71, v39, v74
	v_lshl_add_u32 v71, v71, 2, s33
	v_cndmask_b32_e64 v71, v92, v71, s[58:59]
	ds_read_b32 v112, v71 offset:512
	v_not_b32_e32 v8, v74
	v_add_u32_e32 v72, v41, v8
	v_cmp_gt_u32_e32 vcc, s76, v72
	s_and_b64 s[58:59], vcc, s[28:29]
	v_add_u32_e32 v8, v39, v8
	v_lshl_add_u32 v8, v8, 2, s33
	v_cndmask_b32_e64 v8, v92, v8, s[58:59]
	ds_read_b32 v113, v8 offset:512
	v_or_b32_e32 v8, 2, v74
	v_sub_u32_e32 v9, v41, v8
	v_cmp_gt_u32_e32 vcc, s76, v9
	s_and_b64 s[58:59], vcc, s[28:29]
	v_mov_b32_e32 v72, 0xff800000
	v_mov_b32_e32 v73, 0xff800000
	v_sub_u32_e32 v8, v39, v8
	v_lshl_add_u32 v8, v8, 2, s33
	v_cndmask_b32_e64 v8, v92, v8, s[58:59]
	ds_read_b32 v114, v8 offset:512
	v_or_b32_e32 v8, 3, v74
	v_sub_u32_e32 v9, v41, v8
	v_cmp_gt_u32_e32 vcc, s76, v9
	s_and_b64 s[34:35], vcc, s[28:29]
	v_sub_u32_e32 v8, v39, v8
	v_lshl_add_u32 v8, v8, 2, s33
	v_cndmask_b32_e64 v8, v92, v8, s[34:35]
	ds_read_b32 v115, v8 offset:512
	s_add_i32 s57, s36, 5
	s_lshl_b32 s34, s57, 4
	v_or_b32_e32 v8, s34, v181
	v_mad_u64_u32 v[74:75], s[28:29], v8, s99, v[18:19]
	ds_read_b128 v[8:11], v74
	ds_read_b128 v[74:77], v74 offset:64
	v_or_b32_e32 v78, s34, v54
	s_cmp_gt_u32 s36, 2
	s_cselect_b64 s[28:29], -1, 0
	s_or_b64 s[28:29], s[0:1], s[28:29]
	s_waitcnt lgkmcnt(1)
	v_mfma_f32_16x16x32_bf16 v[8:11], v[8:11], v[4:7], 0
	s_waitcnt lgkmcnt(0)
	v_mfma_f32_16x16x32_bf16 v[8:11], v[74:77], v[0:3], v[8:11]
	s_nop 7
	v_mov_b32_e32 v167, v8
	v_mov_b32_e32 v168, v9
	v_mov_b32_e32 v169, v10
	v_mov_b32_e32 v170, v11
	v_sub_u32_e32 v74, v41, v78
	v_cmp_gt_u32_e32 vcc, s76, v74
	s_and_b64 s[58:59], vcc, s[28:29]
	v_mov_b32_e32 v74, 0xff800000
	v_mov_b32_e32 v75, 0xff800000
	v_sub_u32_e32 v75, v39, v78
	v_lshl_add_u32 v75, v75, 2, s33
	v_cndmask_b32_e64 v75, v92, v75, s[58:59]
	ds_read_b32 v116, v75 offset:512
	v_not_b32_e32 v8, v78
	v_add_u32_e32 v76, v41, v8
	v_cmp_gt_u32_e32 vcc, s76, v76
	s_and_b64 s[58:59], vcc, s[28:29]
	v_add_u32_e32 v8, v39, v8
	v_lshl_add_u32 v8, v8, 2, s33
	v_cndmask_b32_e64 v8, v92, v8, s[58:59]
	ds_read_b32 v117, v8 offset:512
	v_or_b32_e32 v8, 2, v78
	v_sub_u32_e32 v9, v41, v8
	v_cmp_gt_u32_e32 vcc, s76, v9
	s_and_b64 s[58:59], vcc, s[28:29]
	v_mov_b32_e32 v76, 0xff800000
	v_mov_b32_e32 v77, 0xff800000
	v_sub_u32_e32 v8, v39, v8
	v_lshl_add_u32 v8, v8, 2, s33
	v_cndmask_b32_e64 v8, v92, v8, s[58:59]
	ds_read_b32 v118, v8 offset:512
	v_or_b32_e32 v8, 3, v78
	v_sub_u32_e32 v9, v41, v8
	v_cmp_gt_u32_e32 vcc, s76, v9
	s_and_b64 s[34:35], vcc, s[28:29]
	v_sub_u32_e32 v8, v39, v8
	v_lshl_add_u32 v8, v8, 2, s33
	v_cndmask_b32_e64 v8, v92, v8, s[34:35]
	ds_read_b32 v119, v8 offset:512
	s_add_i32 s58, s36, 6
	s_lshl_b32 s34, s58, 4
	v_or_b32_e32 v8, s34, v181
	v_mad_u64_u32 v[78:79], s[28:29], v8, s99, v[18:19]
	ds_read_b128 v[8:11], v78
	ds_read_b128 v[78:81], v78 offset:64
	v_or_b32_e32 v82, s34, v54
	s_cmp_gt_u32 s36, 1
	s_cselect_b64 s[28:29], -1, 0
	s_or_b64 s[28:29], s[0:1], s[28:29]
	s_waitcnt lgkmcnt(1)
	v_mfma_f32_16x16x32_bf16 v[8:11], v[8:11], v[4:7], 0
	s_waitcnt lgkmcnt(0)
	v_mfma_f32_16x16x32_bf16 v[8:11], v[78:81], v[0:3], v[8:11]
	s_nop 7
	v_mov_b32_e32 v171, v8
	v_mov_b32_e32 v172, v9
	v_mov_b32_e32 v173, v10
	v_mov_b32_e32 v174, v11
	v_sub_u32_e32 v78, v41, v82
	v_cmp_gt_u32_e32 vcc, s76, v78
	s_and_b64 s[62:63], vcc, s[28:29]
	v_mov_b32_e32 v78, 0xff800000
	v_mov_b32_e32 v79, 0xff800000
	v_sub_u32_e32 v79, v39, v82
	v_lshl_add_u32 v79, v79, 2, s33
	v_cndmask_b32_e64 v79, v92, v79, s[62:63]
	ds_read_b32 v120, v79 offset:512
	v_not_b32_e32 v8, v82
	v_add_u32_e32 v80, v41, v8
	v_cmp_gt_u32_e32 vcc, s76, v80
	s_and_b64 s[62:63], vcc, s[28:29]
	v_add_u32_e32 v8, v39, v8
	v_lshl_add_u32 v8, v8, 2, s33
	v_cndmask_b32_e64 v8, v92, v8, s[62:63]
	ds_read_b32 v121, v8 offset:512
	v_or_b32_e32 v8, 2, v82
	v_sub_u32_e32 v9, v41, v8
	v_cmp_gt_u32_e32 vcc, s76, v9
	s_and_b64 s[62:63], vcc, s[28:29]
	v_mov_b32_e32 v80, 0xff800000
	v_mov_b32_e32 v81, 0xff800000
	v_sub_u32_e32 v8, v39, v8
	v_lshl_add_u32 v8, v8, 2, s33
	v_cndmask_b32_e64 v8, v92, v8, s[62:63]
	ds_read_b32 v122, v8 offset:512
	v_or_b32_e32 v8, 3, v82
	v_sub_u32_e32 v9, v41, v8
	v_cmp_gt_u32_e32 vcc, s76, v9
	s_and_b64 s[34:35], vcc, s[28:29]
	v_sub_u32_e32 v8, v39, v8
	v_lshl_add_u32 v8, v8, 2, s33
	v_cndmask_b32_e64 v8, v92, v8, s[34:35]
	ds_read_b32 v123, v8 offset:512
	s_add_i32 s59, s36, 7
	s_lshl_b32 s34, s59, 4
	v_or_b32_e32 v8, s34, v181
	v_mad_u64_u32 v[82:83], s[28:29], v8, s99, v[18:19]
	ds_read_b128 v[8:11], v82
	ds_read_b128 v[82:85], v82 offset:64
	v_or_b32_e32 v86, s34, v54
	s_or_b32 s28, s19, s36
	s_cmp_lg_u32 s28, 0
	s_cselect_b64 s[28:29], -1, 0
	s_waitcnt lgkmcnt(1)
	v_mfma_f32_16x16x32_bf16 v[8:11], v[8:11], v[4:7], 0
	s_waitcnt lgkmcnt(0)
	v_mfma_f32_16x16x32_bf16 v[8:11], v[82:85], v[0:3], v[8:11]
	s_nop 7
	v_mov_b32_e32 v175, v8
	v_mov_b32_e32 v176, v9
	v_mov_b32_e32 v177, v10
	v_mov_b32_e32 v178, v11
	v_sub_u32_e32 v82, v41, v86
	v_cmp_gt_u32_e32 vcc, s76, v82
	s_and_b64 s[62:63], vcc, s[28:29]
	v_mov_b32_e32 v82, 0xff800000
	v_mov_b32_e32 v83, 0xff800000
	v_sub_u32_e32 v83, v39, v86
	v_lshl_add_u32 v83, v83, 2, s33
	v_cndmask_b32_e64 v83, v92, v83, s[62:63]
	ds_read_b32 v126, v83 offset:512
	v_not_b32_e32 v8, v86
	v_add_u32_e32 v84, v41, v8
	v_cmp_gt_u32_e32 vcc, s76, v84
	s_and_b64 s[62:63], vcc, s[28:29]
	v_add_u32_e32 v8, v39, v8
	v_lshl_add_u32 v8, v8, 2, s33
	v_cndmask_b32_e64 v8, v92, v8, s[62:63]
	ds_read_b32 v127, v8 offset:512
	v_or_b32_e32 v8, 2, v86
	v_sub_u32_e32 v9, v41, v8
	v_cmp_gt_u32_e32 vcc, s76, v9
	s_and_b64 s[62:63], vcc, s[28:29]
	v_mov_b32_e32 v84, 0xff800000
	v_mov_b32_e32 v85, 0xff800000
	v_sub_u32_e32 v8, v39, v8
	v_lshl_add_u32 v8, v8, 2, s33
	v_cndmask_b32_e64 v8, v92, v8, s[62:63]
	ds_read_b32 v128, v8 offset:512
	v_or_b32_e32 v8, 3, v86
	v_sub_u32_e32 v9, v41, v8
	v_cmp_gt_u32_e32 vcc, s76, v9
	s_and_b64 s[34:35], vcc, s[28:29]
	v_sub_u32_e32 v8, v39, v8
	v_lshl_add_u32 v8, v8, 2, s33
	v_cndmask_b32_e64 v8, v92, v8, s[34:35]
	ds_read_b32 v129, v8 offset:512
	s_add_i32 s34, s36, 8
	s_lshl_b32 s35, s34, 4
	v_or_b32_e32 v8, s35, v181
	v_mad_u64_u32 v[86:87], s[28:29], v8, s99, v[18:19]
	ds_read_b128 v[8:11], v86
	v_mov_b32_e32 v87, 0xff800000
	s_waitcnt lgkmcnt(0)
	v_mfma_f32_16x16x32_bf16 v[4:7], v[8:11], v[4:7], 0
	ds_read_b128 v[8:11], v86 offset:64
	v_mov_b32_e32 v86, 0xff800000
	s_waitcnt lgkmcnt(0)
	v_mfma_f32_16x16x32_bf16 v[0:3], v[8:11], v[0:3], v[4:7]
	s_nop 7
	v_mov_b32_e32 v179, v0
	v_mov_b32_e32 v182, v1
	v_mov_b32_e32 v183, v2
	v_mov_b32_e32 v184, v3
	s_nop 3
	v_or_b32_e32 v4, s35, v54
	v_sub_u32_e32 v5, v41, v4
	v_cmp_gt_u32_e32 vcc, s76, v5
	v_sub_u32_e32 v5, v39, v4
	v_lshl_add_u32 v5, v5, 2, s33
	s_nop 1
	v_cndmask_b32_e64 v5, v92, v5, vcc
	ds_read_b32 v130, v5 offset:512
	v_not_b32_e32 v0, v4
	v_add_u32_e32 v5, v41, v0
	v_cmp_gt_u32_e32 vcc, s76, v5
	v_add_u32_e32 v0, v39, v0
	v_lshl_add_u32 v0, v0, 2, s33
	s_nop 1
	v_cndmask_b32_e64 v0, v92, v0, vcc
	ds_read_b32 v131, v0 offset:512
	v_or_b32_e32 v0, 2, v4
	v_sub_u32_e32 v1, v41, v0
	v_cmp_gt_u32_e32 vcc, s76, v1
	v_mov_b32_e32 v88, 0xff800000
	v_mov_b32_e32 v89, 0xff800000
	v_sub_u32_e32 v0, v39, v0
	v_lshl_add_u32 v0, v0, 2, s33
	s_nop 1
	v_cndmask_b32_e64 v0, v92, v0, vcc
	ds_read_b32 v132, v0 offset:512
	v_or_b32_e32 v0, 3, v4
	v_sub_u32_e32 v1, v41, v0
	v_cmp_gt_u32_e32 vcc, s76, v1
	v_sub_u32_e32 v0, v39, v0
	v_lshl_add_u32 v0, v0, 2, s33
	s_nop 1
	v_cndmask_b32_e64 v0, v92, v0, vcc
	ds_read_b32 v133, v0 offset:512
	s_waitcnt lgkmcnt(0)
	v_fmamk_f32 v40, v147, 0x3e000000, v96
	v_fmamk_f32 v38, v148, 0x3e000000, v97
	v_fmamk_f32 v43, v149, 0x3e000000, v98
	v_fmamk_f32 v42, v150, 0x3e000000, v99
	v_fmamk_f32 v45, v151, 0x3e000000, v100
	v_fmamk_f32 v44, v152, 0x3e000000, v101
	v_fmamk_f32 v47, v153, 0x3e000000, v102
	v_fmamk_f32 v46, v154, 0x3e000000, v103
	v_fmamk_f32 v49, v155, 0x3e000000, v104
	v_fmamk_f32 v48, v156, 0x3e000000, v105
	v_fmamk_f32 v51, v157, 0x3e000000, v106
	v_fmamk_f32 v50, v158, 0x3e000000, v107
	v_fmamk_f32 v53, v159, 0x3e000000, v108
	v_fmamk_f32 v52, v160, 0x3e000000, v109
	v_fmamk_f32 v69, v161, 0x3e000000, v110
	v_fmamk_f32 v68, v162, 0x3e000000, v111
	v_fmamk_f32 v71, v163, 0x3e000000, v112
	v_fmamk_f32 v70, v164, 0x3e000000, v113
	v_fmamk_f32 v73, v165, 0x3e000000, v114
	v_fmamk_f32 v72, v166, 0x3e000000, v115
	v_fmamk_f32 v75, v167, 0x3e000000, v116
	v_fmamk_f32 v74, v168, 0x3e000000, v117
	v_fmamk_f32 v77, v169, 0x3e000000, v118
	v_fmamk_f32 v76, v170, 0x3e000000, v119
	v_fmamk_f32 v79, v171, 0x3e000000, v120
	v_fmamk_f32 v78, v172, 0x3e000000, v121
	v_fmamk_f32 v81, v173, 0x3e000000, v122
	v_fmamk_f32 v80, v174, 0x3e000000, v123
	v_fmamk_f32 v83, v175, 0x3e000000, v126
	v_fmamk_f32 v82, v176, 0x3e000000, v127
	v_fmamk_f32 v85, v177, 0x3e000000, v128
	v_fmamk_f32 v84, v178, 0x3e000000, v129
	v_fmamk_f32 v87, v179, 0x3e000000, v130
	v_fmamk_f32 v86, v182, 0x3e000000, v131
	v_fmamk_f32 v89, v183, 0x3e000000, v132
	v_fmamk_f32 v88, v184, 0x3e000000, v133
	s_branch .LBB0_61

.LBB0_149:
	v_add_u32_e32 v218, 0x10800, v123
	ds_read_b64 v[218:219], v218
	v_add_u32_e32 v232, 0x11900, v123
	ds_read_b64 v[232:233], v232
	v_add_u32_e32 v234, 0x12a00, v123
	ds_read_b64 v[234:235], v234
	v_add_u32_e32 v238, 0x13b00, v123
	ds_read_b64 v[238:239], v238
	v_add_u32_e32 v161, 0, v121
	ds_read_b128 v[206:209], v161 offset:192
	ds_read_b128 v[210:213], v161 offset:128
	ds_read_b128 v[214:217], v161 offset:64
	ds_read_b128 v[240:243], v161
	v_cmp_ge_u32_e64 s[0:1], v128, v122
	s_add_i32 s24, s24, -1
	s_cmp_lg_u32 s24, 0
	s_waitcnt lgkmcnt(0)
	s_waitcnt vmcnt(17)
	v_mfma_f32_16x16x32_bf16 v[240:243], v[240:243], v[28:31], 0
	s_waitcnt vmcnt(16)
	v_mfma_f32_16x16x32_bf16 v[214:217], v[214:217], v[24:27], 0
	s_waitcnt vmcnt(15)
	v_mfma_f32_16x16x32_bf16 v[210:213], v[210:213], v[20:23], v[240:243]
	s_waitcnt vmcnt(14)
	v_mfma_f32_16x16x32_bf16 v[206:209], v[206:209], v[16:19], v[214:217]
	s_nop 3
	ds_read_b128 v[214:217], v161 offset:448
	ds_read_b128 v[240:243], v161 offset:384
	ds_read_b128 v[244:247], v161 offset:320
	ds_read_b128 v[248:251], v161 offset:256
	s_waitcnt lgkmcnt(0)
	s_waitcnt vmcnt(13)
	v_mfma_f32_16x16x32_bf16 v[210:213], v[248:251], v[12:15], v[210:213]
	v_mul_f32_e32 v161, v120, v201
	s_waitcnt vmcnt(12)
	v_mfma_f32_16x16x32_bf16 v[206:209], v[244:247], v[8:11], v[206:209]
	s_waitcnt vmcnt(11)
	v_mfma_f32_16x16x32_bf16 v[210:213], v[240:243], v[4:7], v[210:213]
	s_waitcnt vmcnt(10)
	v_mfma_f32_16x16x32_bf16 v[206:209], v[214:217], v[0:3], v[206:209]
	s_nop 7
	v_pk_add_f32 v[206:207], v[210:211], v[206:207]
	v_pk_add_f32 v[178:179], v[212:213], v[208:209]
	v_mul_f32_e32 v161, v206, v161
	v_mul_f32_e32 v206, v120, v202
	v_cndmask_b32_e64 v161, 0, v161, s[0:1]
	v_cmp_gt_u32_e64 s[0:1], v128, v122
	v_mul_f32_e32 v206, v207, v206
	v_or_b32_e32 v210, 2, v122
	v_cndmask_b32_e64 v208, 0, v206, s[0:1]
	v_pk_mul_f32 v[206:207], v[120:121], v[164:165] op_sel_hi:[0,1]
	v_pk_mul_f32 v[178:179], v[178:179], v[206:207]
	v_or_b32_e32 v209, 3, v122
	v_cvt_pk_bf16_f32 v206, v161, v208
	v_cvt_pk_bf16_f32 v161, v178, v179
	v_cmp_ge_u32_e64 s[0:1], v158, v210
	v_mul_f32_e32 v120, v204, v120
	v_add_u32_e32 v122, 16, v122
	v_cndmask_b32_e64 v178, 0, v161, s[0:1]
	v_lshrrev_b32_e32 v161, 16, v161
	v_cmp_ge_u32_e64 s[0:1], v125, v209
	v_add_u32_e32 v121, 0x2100, v121
	s_nop 0
	v_cndmask_b32_e64 v161, 0, v161, s[0:1]
	v_perm_b32 v207, v161, v178, s20
	v_add_u32_e32 v123, 32, v123
	s_waitcnt lgkmcnt(0)
	s_nop 1
	v_mfma_f32_16x16x16_bf16 v[116:119], v[218:219], v[206:207], v[116:119]
	v_mfma_f32_16x16x16_bf16 v[112:115], v[232:233], v[206:207], v[112:115]
	v_mfma_f32_16x16x16_bf16 v[108:111], v[234:235], v[206:207], v[108:111]
	v_mfma_f32_16x16x16_bf16 v[104:107], v[238:239], v[206:207], v[104:107]
	s_cbranch_scc1 .LBB0_149
	v_lshl_add_u64 v[178:179], s[34:35], 0, v[128:129]
	v_mad_u64_u32 v[218:219], s[0:1], v178, s86, v[176:177]
	v_mov_b32_e32 v232, v219
	v_mad_u64_u32 v[232:233], s[0:1], v179, s86, v[232:233]
	v_mov_b32_e32 v219, v232
	ds_read_b128 v[232:235], v199
	ds_read_b128 v[214:217], v199 offset:64
	s_waitcnt lgkmcnt(1)
	v_mfma_f32_16x16x32_bf16 v[120:123], v[232:235], v[28:31], 0
	ds_read_b128 v[232:235], v199 offset:128
	s_waitcnt lgkmcnt(1)
	v_mfma_f32_16x16x32_bf16 v[120:123], v[214:217], v[24:27], v[120:123]
	ds_read_b128 v[214:217], v199 offset:192
	s_waitcnt lgkmcnt(1)
	v_mfma_f32_16x16x32_bf16 v[120:123], v[232:235], v[20:23], v[120:123]
	ds_read_b128 v[232:235], v199 offset:256
	s_waitcnt lgkmcnt(1)
	v_mfma_f32_16x16x32_bf16 v[120:123], v[214:217], v[16:19], v[120:123]
	ds_read_b128 v[214:217], v199 offset:320
	s_waitcnt lgkmcnt(1)
	v_mfma_f32_16x16x32_bf16 v[120:123], v[232:235], v[12:15], v[120:123]
	ds_read_b128 v[232:235], v199 offset:384
	s_waitcnt lgkmcnt(1)
	v_mfma_f32_16x16x32_bf16 v[120:123], v[214:217], v[8:11], v[120:123]
	ds_read_b128 v[214:217], v199 offset:448
	s_waitcnt lgkmcnt(1)
	v_mfma_f32_16x16x32_bf16 v[120:123], v[232:235], v[4:7], v[120:123]
	s_waitcnt lgkmcnt(0)
	v_mfma_f32_16x16x32_bf16 v[120:123], v[214:217], v[0:3], v[120:123]
	ds_read_b128 v[232:235], v199 offset:8448
	ds_read_b128 v[214:217], v199 offset:8512
	s_waitcnt lgkmcnt(1)
	v_mfma_f32_16x16x32_bf16 v[206:209], v[232:235], v[28:31], 0
	ds_read_b128 v[232:235], v199 offset:8576
	s_waitcnt lgkmcnt(1)
	v_mfma_f32_16x16x32_bf16 v[206:209], v[214:217], v[24:27], v[206:209]
	ds_read_b128 v[214:217], v199 offset:8640
	s_waitcnt lgkmcnt(1)
	v_mfma_f32_16x16x32_bf16 v[206:209], v[232:235], v[20:23], v[206:209]
	ds_read_b128 v[232:235], v199 offset:8704
	s_waitcnt lgkmcnt(1)
	v_mfma_f32_16x16x32_bf16 v[206:209], v[214:217], v[16:19], v[206:209]
	ds_read_b128 v[214:217], v199 offset:8768
	v_pk_fma_f32 v[118:119], v[174:175], v[122:123], v[118:119]
	v_fma_f32 v116, v168, v120, v116
	v_fma_f32 v117, v169, v121, v117
	v_add_f32_e32 v121, v118, v119
	v_add_f32_e32 v120, v116, v117
	v_add_f32_e32 v120, v120, v121
	v_mul_f32_e32 v121, v117, v117
	v_fmac_f32_e32 v121, v116, v116
	v_cvt_pk_bf16_f32 v116, v116, v117
	v_cvt_pk_bf16_f32 v117, v118, v119
	v_mul_f32_e32 v122, v119, v119
	v_fmac_f32_e32 v122, v118, v118
	v_add_f32_e32 v120, 0, v120
	v_add_f32_e32 v121, v121, v122
	s_waitcnt lgkmcnt(1)
	v_mfma_f32_16x16x32_bf16 v[206:209], v[232:235], v[12:15], v[206:209]
	ds_read_b128 v[232:235], v199 offset:8832
	s_waitcnt lgkmcnt(1)
	v_mfma_f32_16x16x32_bf16 v[206:209], v[214:217], v[8:11], v[206:209]
	ds_read_b128 v[214:217], v199 offset:8896
	s_waitcnt lgkmcnt(1)
	v_mfma_f32_16x16x32_bf16 v[206:209], v[232:235], v[4:7], v[206:209]
	s_waitcnt lgkmcnt(0)
	v_mfma_f32_16x16x32_bf16 v[206:209], v[214:217], v[0:3], v[206:209]
	ds_read_b128 v[232:235], v199 offset:16896
	ds_read_b128 v[214:217], v199 offset:16960
	s_waitcnt lgkmcnt(1)
	v_mfma_f32_16x16x32_bf16 v[210:213], v[232:235], v[28:31], 0
	ds_read_b128 v[232:235], v199 offset:17024
	s_waitcnt lgkmcnt(1)
	v_mfma_f32_16x16x32_bf16 v[210:213], v[214:217], v[24:27], v[210:213]
	ds_read_b128 v[214:217], v199 offset:17088
	s_waitcnt lgkmcnt(1)
	v_mfma_f32_16x16x32_bf16 v[210:213], v[232:235], v[20:23], v[210:213]
	ds_read_b128 v[232:235], v199 offset:17152
	s_waitcnt lgkmcnt(1)
	v_mfma_f32_16x16x32_bf16 v[210:213], v[214:217], v[16:19], v[210:213]
	ds_read_b128 v[214:217], v199 offset:17216
	v_pk_fma_f32 v[114:115], v[174:175], v[208:209], v[114:115]
	v_fma_f32 v112, v168, v206, v112
	v_fma_f32 v113, v169, v207, v113
	v_mul_f32_e32 v118, v115, v115
	v_fmac_f32_e32 v118, v114, v114
	s_waitcnt lgkmcnt(1)
	v_mfma_f32_16x16x32_bf16 v[210:213], v[232:235], v[12:15], v[210:213]
	ds_read_b128 v[232:235], v199 offset:17280
	s_waitcnt lgkmcnt(1)
	v_mfma_f32_16x16x32_bf16 v[210:213], v[214:217], v[8:11], v[210:213]
	ds_read_b128 v[214:217], v199 offset:17344
	s_waitcnt lgkmcnt(1)
	v_mfma_f32_16x16x32_bf16 v[210:213], v[232:235], v[4:7], v[210:213]
	s_waitcnt lgkmcnt(0)
	v_mfma_f32_16x16x32_bf16 v[210:213], v[214:217], v[0:3], v[210:213]
	ds_read_b128 v[232:235], v199 offset:25344
	ds_read_b128 v[206:209], v199 offset:25408
	s_waitcnt lgkmcnt(1)
	v_mfma_f32_16x16x32_bf16 v[214:217], v[232:235], v[28:31], 0
	ds_read_b128 v[232:235], v199 offset:25472
	s_waitcnt lgkmcnt(1)
	v_mfma_f32_16x16x32_bf16 v[214:217], v[206:209], v[24:27], v[214:217]
	ds_read_b128 v[206:209], v199 offset:25536
	s_waitcnt lgkmcnt(1)
	v_mfma_f32_16x16x32_bf16 v[214:217], v[232:235], v[20:23], v[214:217]
	ds_read_b128 v[232:235], v199 offset:25600
	s_waitcnt lgkmcnt(1)
	v_mfma_f32_16x16x32_bf16 v[214:217], v[206:209], v[16:19], v[214:217]
	ds_read_b128 v[206:209], v199 offset:25664
	v_pk_fma_f32 v[110:111], v[174:175], v[212:213], v[110:111]
	v_pk_fma_f32 v[108:109], v[168:169], v[210:211], v[108:109]
	s_waitcnt lgkmcnt(1)
	v_mfma_f32_16x16x32_bf16 v[214:217], v[232:235], v[12:15], v[214:217]
	ds_read_b128 v[232:235], v199 offset:25728
	s_waitcnt lgkmcnt(1)
	v_mfma_f32_16x16x32_bf16 v[214:217], v[206:209], v[8:11], v[214:217]
	ds_read_b128 v[206:209], v199 offset:25792
	s_waitcnt lgkmcnt(1)
	v_mfma_f32_16x16x32_bf16 v[214:217], v[232:235], v[4:7], v[214:217]
	s_waitcnt lgkmcnt(0)
	v_mfma_f32_16x16x32_bf16 v[214:217], v[206:209], v[0:3], v[214:217]
	s_nop 7
	v_lshl_add_u64 v[0:1], s[36:37], 0, v[128:129]
	v_mad_u64_u32 v[2:3], s[0:1], v0, s86, v[172:173]
	v_mov_b32_e32 v0, v3
	v_mad_u64_u32 v[0:1], s[0:1], v1, s86, v[0:1]
	v_mov_b32_e32 v3, v0
	global_load_dwordx4 v[28:31], v[2:3], off
	global_load_dwordx4 v[24:27], v[2:3], off offset:64
	global_load_dwordx4 v[20:23], v[2:3], off offset:128
	global_load_dwordx4 v[16:19], v[2:3], off offset:192
	global_load_dwordx4 v[12:15], v[2:3], off offset:256
	global_load_dwordx4 v[8:11], v[2:3], off offset:320
	global_load_dwordx4 v[4:7], v[2:3], off offset:384
	s_nop 0
	global_load_dwordx4 v[0:3], v[2:3], off offset:448
	v_pk_fma_f32 v[106:107], v[174:175], v[216:217], v[106:107]
	global_store_dwordx2 v[218:219], v[116:117], off
	v_add_f32_e32 v116, v112, v113
	v_add_f32_e32 v117, v114, v115
	v_add_f32_e32 v116, v116, v117
	v_mul_f32_e32 v117, v113, v113
	v_fmac_f32_e32 v117, v112, v112
	v_cvt_pk_bf16_f32 v112, v112, v113
	v_cvt_pk_bf16_f32 v113, v114, v115
	global_store_dwordx2 v[218:219], v[112:113], off offset:32
	v_add_f32_e32 v112, v108, v109
	v_add_f32_e32 v113, v110, v111
	v_add_f32_e32 v112, v112, v113
	v_mul_f32_e32 v113, v109, v109
	v_fmac_f32_e32 v113, v108, v108
	v_cvt_pk_bf16_f32 v108, v108, v109
	v_cvt_pk_bf16_f32 v109, v110, v111
	v_pk_fma_f32 v[104:105], v[168:169], v[214:215], v[104:105]
	v_mul_f32_e32 v114, v111, v111
	global_store_dwordx2 v[218:219], v[108:109], off offset:64
	v_add_f32_e32 v108, v104, v105
	v_add_f32_e32 v109, v106, v107
	v_add_f32_e32 v117, v117, v118
	v_fmac_f32_e32 v114, v110, v110
	v_add_f32_e32 v108, v108, v109
	v_mul_f32_e32 v109, v105, v105
	v_mul_f32_e32 v110, v107, v107
	v_add_f32_e32 v116, v120, v116
	v_add_f32_e32 v117, v121, v117
	v_add_f32_e32 v113, v113, v114
	v_fmac_f32_e32 v109, v104, v104
	v_fmac_f32_e32 v110, v106, v106
	v_add_f32_e32 v112, v116, v112
	v_add_f32_e32 v113, v117, v113
	v_add_f32_e32 v109, v109, v110
	v_add_f32_e32 v108, v112, v108
	v_add_f32_e32 v109, v113, v109
	v_cvt_pk_bf16_f32 v104, v104, v105
	v_cvt_pk_bf16_f32 v105, v106, v107
	global_store_dwordx2 v[218:219], v[104:105], off offset:96
	v_mov_b32_e32 v104, v108
	v_mov_b32_e32 v105, v109
	s_nop 0
	v_permlane16_swap_b32_e32 v108, v104
	v_permlane16_swap_b32_e32 v109, v105
	v_add_f32_e32 v104, v108, v104
	v_add_f32_e32 v105, v109, v105
	v_mov_b32_e32 v106, v104
	v_mov_b32_e32 v107, v105
	s_nop 0
	v_permlane32_swap_b32_e32 v104, v106
	v_permlane32_swap_b32_e32 v105, v107
	s_and_saveexec_b64 s[0:1], s[38:39]
	s_cbranch_execz .LBB0_147
	v_pk_add_f32 v[104:105], v[104:105], v[106:107]
	v_lshlrev_b64 v[106:107], 8, v[178:179]
	v_lshl_add_u64 v[106:107], s[28:29], 0, v[106:107]
	global_store_dwordx2 v[106:107], v[104:105], off
	s_branch .LBB0_147
